# RG-LRU causal conv loop rewritten: 16 tap loads in flight per iteration, wave-uniform boundary handling (was 3-4 serialized round trips per iteration)
# baseline (speedup 1.0000x reference)
; __global__ void __launch_bounds__(512, 2) mega_fwd(Params P) {
;     ...
;                     { const float* cw = P.in[14] + (size_t)hl * 4 * 512; const float* cbs = P.in[15] + (size_t)hl * 512;
;                       const int c0 = (int)(gtid & 63) * 8;
;                       f32x4 wv[4][2], bb[2];
; #pragma unroll
;                       for (int j = 0; j < 4; ++j) { wv[j][0] = *(const f32x4*)(cw + j * 512 + c0); wv[j][1] = *(const f32x4*)(cw + j * 512 + c0 + 4); }
;                       bb[0] = *(const f32x4*)(cbs + c0); bb[1] = *(const f32x4*)(cbs + c0 + 4);
;                       for (size_t idx0 = gtid; idx0 < (size_t)T_TOK * 64; idx0 += GT * 4) {
;                         u32x4 xv[4][4];
; #pragma unroll
;                         for (int q = 0; q < 4; ++q) { const size_t idx = idx0 + (size_t)q * GT; const bool ok = idx < (size_t)T_TOK * 64; const int row = ok ? (int)(idx >> 6) : 3, pos = row & (SEQ - 1);
; #pragma unroll
;                             for (int j = 0; j < 4; ++j) xv[q][j] = (pos - 3 + j >= 0) ? *(const u32x4*)(Z + (size_t)(row - 3 + j) * ZW + 2048 + c0) : (u32x4){0u, 0u, 0u, 0u}; }
.LBB0_923:
	s_or_b64 exec, exec, s[14:15]
	v_cmp_gt_u64_e32 vcc, s[46:47], v[106:107]
	s_and_saveexec_b64 s[40:41], vcc
	s_cbranch_execz .LBB0_956
	s_ashr_i32 s2, s1, 1
	v_readlane_b32 s4, v254, 37
	v_readlane_b32 s5, v254, 38
	s_lshl_b32 s3, s2, 13
	s_add_u32 s4, s4, s3
	s_addc_u32 s5, s5, 0
	v_readlane_b32 s6, v254, 39
	v_readlane_b32 s7, v254, 40
	s_lshl_b32 s3, s2, 11
	s_add_u32 s6, s6, s3
	s_addc_u32 s7, s7, 0
	v_and_b32_e32 v0, 63, v211
	v_lshlrev_b32_e32 v2, 5, v0
	v_lshlrev_b32_e32 v3, 4, v0
	global_load_dwordx4 v[4:7], v2, s[4:5]
	global_load_dwordx4 v[8:11], v2, s[4:5] offset:16
	global_load_dwordx4 v[12:15], v2, s[4:5] offset:2048
	global_load_dwordx4 v[16:19], v2, s[4:5] offset:2064
	s_add_u32 s12, s4, 0x1000
	s_addc_u32 s13, s5, 0
	global_load_dwordx4 v[20:23], v2, s[12:13]
	global_load_dwordx4 v[24:27], v2, s[12:13] offset:16
	global_load_dwordx4 v[28:31], v2, s[12:13] offset:2048
	global_load_dwordx4 v[32:35], v2, s[12:13] offset:2064
	global_load_dwordx4 v[36:39], v2, s[6:7]
	global_load_dwordx4 v[40:43], v2, s[6:7] offset:16
	s_add_u32 s2, s44, 0x15801000
	s_addc_u32 s3, s45, 0
	s_add_u32 s4, s44, 0x3b800000
	s_addc_u32 s5, s45, 0
	v_readfirstlane_b32 s6, v211
	s_and_b32 s6, s6, 0xffffffc0
	v_readlane_b32 s7, v254, 0
	s_lshl_b32 s7, s7, 9
	s_add_u32 s6, s6, s7
	v_readlane_b32 s7, v254, 7
	s_lshl_b32 s7, s7, 9
	s_cmp_lt_u32 s6, 0x400000
	s_cbranch_scc0 .Lmyconv_done
.Lmyconv_loop:
	s_mov_b32 s12, s6
	s_cmp_ge_u32 s12, 0x400000
	s_cbranch_scc1 .Lmyconv_ldskip0
	s_lshr_b32 s13, s12, 6
	s_and_b32 s20, s13, 0x7ff
	s_sub_u32 s21, s13, 3
	s_mul_i32 s21, s21, 0x1400
	s_ashr_i32 s24, s21, 31
	s_add_u32 s22, s2, s21
	s_addc_u32 s23, s3, s24
	s_add_u32 s24, s20, 0
	s_cmp_lt_u32 s24, 3
	s_cbranch_scc1 .Lmyconv_z00
	global_load_dwordx4 v[44:47], v3, s[22:23]
	s_branch .Lmyconv_n00
.Lmyconv_z00:
	v_mov_b32_e32 v44, 0
	v_mov_b32_e32 v45, 0
	v_mov_b32_e32 v46, 0
	v_mov_b32_e32 v47, 0
.Lmyconv_n00:
	s_add_u32 s22, s22, 0x1400
	s_addc_u32 s23, s23, 0
	s_add_u32 s24, s20, 1
	s_cmp_lt_u32 s24, 3
	s_cbranch_scc1 .Lmyconv_z01
	global_load_dwordx4 v[48:51], v3, s[22:23]
	s_branch .Lmyconv_n01
.Lmyconv_z01:
	v_mov_b32_e32 v48, 0
	v_mov_b32_e32 v49, 0
	v_mov_b32_e32 v50, 0
	v_mov_b32_e32 v51, 0
.Lmyconv_n01:
	s_add_u32 s22, s22, 0x1400
	s_addc_u32 s23, s23, 0
	s_add_u32 s24, s20, 2
	s_cmp_lt_u32 s24, 3
	s_cbranch_scc1 .Lmyconv_z02
	global_load_dwordx4 v[52:55], v3, s[22:23]
	s_branch .Lmyconv_n02
.Lmyconv_z02:
	v_mov_b32_e32 v52, 0
	v_mov_b32_e32 v53, 0
	v_mov_b32_e32 v54, 0
	v_mov_b32_e32 v55, 0
.Lmyconv_n02:
	s_add_u32 s22, s22, 0x1400
	s_addc_u32 s23, s23, 0
	global_load_dwordx4 v[56:59], v3, s[22:23]
.Lmyconv_ldskip0:
	s_add_u32 s12, s12, s7
	s_cmp_ge_u32 s12, 0x400000
	s_cbranch_scc1 .Lmyconv_ldskip1
	s_lshr_b32 s13, s12, 6
	s_and_b32 s20, s13, 0x7ff
	s_sub_u32 s21, s13, 3
	s_mul_i32 s21, s21, 0x1400
	s_ashr_i32 s24, s21, 31
	s_add_u32 s22, s2, s21
	s_addc_u32 s23, s3, s24
	s_add_u32 s24, s20, 0
	s_cmp_lt_u32 s24, 3
	s_cbranch_scc1 .Lmyconv_z10
	global_load_dwordx4 v[60:63], v3, s[22:23]
	s_branch .Lmyconv_n10
.Lmyconv_z10:
	v_mov_b32_e32 v60, 0
	v_mov_b32_e32 v61, 0
	v_mov_b32_e32 v62, 0
	v_mov_b32_e32 v63, 0
.Lmyconv_n10:
	s_add_u32 s22, s22, 0x1400
	s_addc_u32 s23, s23, 0
	s_add_u32 s24, s20, 1
	s_cmp_lt_u32 s24, 3
	s_cbranch_scc1 .Lmyconv_z11
	global_load_dwordx4 v[64:67], v3, s[22:23]
	s_branch .Lmyconv_n11
.Lmyconv_z11:
	v_mov_b32_e32 v64, 0
	v_mov_b32_e32 v65, 0
	v_mov_b32_e32 v66, 0
	v_mov_b32_e32 v67, 0
.Lmyconv_n11:
	s_add_u32 s22, s22, 0x1400
	s_addc_u32 s23, s23, 0
	s_add_u32 s24, s20, 2
	s_cmp_lt_u32 s24, 3
	s_cbranch_scc1 .Lmyconv_z12
	global_load_dwordx4 v[68:71], v3, s[22:23]
	s_branch .Lmyconv_n12
.Lmyconv_z12:
	v_mov_b32_e32 v68, 0
	v_mov_b32_e32 v69, 0
	v_mov_b32_e32 v70, 0
	v_mov_b32_e32 v71, 0
.Lmyconv_n12:
	s_add_u32 s22, s22, 0x1400
	s_addc_u32 s23, s23, 0
	global_load_dwordx4 v[72:75], v3, s[22:23]
.Lmyconv_ldskip1:
	s_add_u32 s12, s12, s7
	s_cmp_ge_u32 s12, 0x400000
	s_cbranch_scc1 .Lmyconv_ldskip2
	s_lshr_b32 s13, s12, 6
	s_and_b32 s20, s13, 0x7ff
	s_sub_u32 s21, s13, 3
	s_mul_i32 s21, s21, 0x1400
	s_ashr_i32 s24, s21, 31
	s_add_u32 s22, s2, s21
	s_addc_u32 s23, s3, s24
	s_add_u32 s24, s20, 0
	s_cmp_lt_u32 s24, 3
	s_cbranch_scc1 .Lmyconv_z20
	global_load_dwordx4 v[76:79], v3, s[22:23]
	s_branch .Lmyconv_n20
.Lmyconv_z20:
	v_mov_b32_e32 v76, 0
	v_mov_b32_e32 v77, 0
	v_mov_b32_e32 v78, 0
	v_mov_b32_e32 v79, 0
.Lmyconv_n20:
	s_add_u32 s22, s22, 0x1400
	s_addc_u32 s23, s23, 0
	s_add_u32 s24, s20, 1
	s_cmp_lt_u32 s24, 3
	s_cbranch_scc1 .Lmyconv_z21
	global_load_dwordx4 v[80:83], v3, s[22:23]
	s_branch .Lmyconv_n21
.Lmyconv_z21:
	v_mov_b32_e32 v80, 0
	v_mov_b32_e32 v81, 0
	v_mov_b32_e32 v82, 0
	v_mov_b32_e32 v83, 0
.Lmyconv_n21:
	s_add_u32 s22, s22, 0x1400
	s_addc_u32 s23, s23, 0
	s_add_u32 s24, s20, 2
	s_cmp_lt_u32 s24, 3
	s_cbranch_scc1 .Lmyconv_z22
	global_load_dwordx4 v[84:87], v3, s[22:23]
	s_branch .Lmyconv_n22
.Lmyconv_z22:
	v_mov_b32_e32 v84, 0
	v_mov_b32_e32 v85, 0
	v_mov_b32_e32 v86, 0
	v_mov_b32_e32 v87, 0
.Lmyconv_n22:
	s_add_u32 s22, s22, 0x1400
	s_addc_u32 s23, s23, 0
	global_load_dwordx4 v[88:91], v3, s[22:23]
.Lmyconv_ldskip2:
	s_add_u32 s12, s12, s7
	s_cmp_ge_u32 s12, 0x400000
	s_cbranch_scc1 .Lmyconv_ldskip3
	s_lshr_b32 s13, s12, 6
	s_and_b32 s20, s13, 0x7ff
	s_sub_u32 s21, s13, 3
	s_mul_i32 s21, s21, 0x1400
	s_ashr_i32 s24, s21, 31
	s_add_u32 s22, s2, s21
	s_addc_u32 s23, s3, s24
	s_add_u32 s24, s20, 0
	s_cmp_lt_u32 s24, 3
	s_cbranch_scc1 .Lmyconv_z30
	global_load_dwordx4 v[92:95], v3, s[22:23]
	s_branch .Lmyconv_n30
.Lmyconv_z30:
	v_mov_b32_e32 v92, 0
	v_mov_b32_e32 v93, 0
	v_mov_b32_e32 v94, 0
	v_mov_b32_e32 v95, 0
; __device__ __forceinline__ unsigned cvt_pk_bf16(float lo, float hi) { unsigned r; asm volatile("v_cvt_pk_bf16_f32 %0, %1, %2" : "=v"(r) : "v"(lo), "v"(hi)); return r; }
; __device__ __forceinline__ float bflo(unsigned w) { return __uint_as_float(w << 16); }
; __device__ __forceinline__ float bfhi(unsigned w) { return __uint_as_float(w & 0xffff0000u); }
; __global__ void __launch_bounds__(512, 2) mega_fwd(Params P) {
;     ...
;                         for (int q = 0; q < 4; ++q) { const size_t idx = idx0 + (size_t)q * GT; const bool ok = idx < (size_t)T_TOK * 64; const int row = ok ? (int)(idx >> 6) : 3, pos = row & (SEQ - 1);
; #pragma unroll
;                             for (int j = 0; j < 4; ++j) xv[q][j] = (pos - 3 + j >= 0) ? *(const u32x4*)(Z + (size_t)(row - 3 + j) * ZW + 2048 + c0) : (u32x4){0u, 0u, 0u, 0u}; }
; #pragma unroll
;                         for (int q = 0; q < 4; ++q) { const size_t idx = idx0 + (size_t)q * GT; if (idx < (size_t)T_TOK * 64) { const int row = (int)(idx >> 6);
;                             f32x4 a0 = bb[0], a1 = bb[1];
; #pragma unroll
;                             for (int j = 0; j < 4; ++j) { const u32x4 v = xv[q][j]; f32x4 x0, x1; x0[0] = bflo(v.x); x0[1] = bfhi(v.x); x0[2] = bflo(v.y); x0[3] = bfhi(v.y); x1[0] = bflo(v.z); x1[1] = bfhi(v.z); x1[2] = bflo(v.w); x1[3] = bfhi(v.w);
;                                 a0 += wv[j][0] * x0; a1 += wv[j][1] * x1; }
;                             u32x4 o; o.x = cvt_pk_bf16(a0[0], a0[1]); o.y = cvt_pk_bf16(a0[2], a0[3]); o.z = cvt_pk_bf16(a1[0], a1[1]); o.w = cvt_pk_bf16(a1[2], a1[3]);
;                             *(u32x4*)(XC + (size_t)row * 512 + c0) = o; } }
.Lmyconv_n30:
	s_add_u32 s22, s22, 0x1400
	s_addc_u32 s23, s23, 0
	s_add_u32 s24, s20, 1
	s_cmp_lt_u32 s24, 3
	s_cbranch_scc1 .Lmyconv_z31
	global_load_dwordx4 v[96:99], v3, s[22:23]
	s_branch .Lmyconv_n31
.Lmyconv_z31:
	v_mov_b32_e32 v96, 0
	v_mov_b32_e32 v97, 0
	v_mov_b32_e32 v98, 0
	v_mov_b32_e32 v99, 0
.Lmyconv_n31:
	s_add_u32 s22, s22, 0x1400
	s_addc_u32 s23, s23, 0
	s_add_u32 s24, s20, 2
	s_cmp_lt_u32 s24, 3
	s_cbranch_scc1 .Lmyconv_z32
	global_load_dwordx4 v[100:103], v3, s[22:23]
	s_branch .Lmyconv_n32
.Lmyconv_z32:
	v_mov_b32_e32 v100, 0
	v_mov_b32_e32 v101, 0
	v_mov_b32_e32 v102, 0
	v_mov_b32_e32 v103, 0
.Lmyconv_n32:
	s_add_u32 s22, s22, 0x1400
	s_addc_u32 s23, s23, 0
	global_load_dwordx4 v[104:107], v3, s[22:23]
.Lmyconv_ldskip3:
	s_waitcnt vmcnt(0)
	s_mov_b32 s12, s6
	s_cmp_ge_u32 s12, 0x400000
	s_cbranch_scc1 .Lmyconv_cskip0
	v_mov_b32_e32 v108, v36
	v_mov_b32_e32 v109, v37
	v_mov_b32_e32 v110, v38
	v_mov_b32_e32 v111, v39
	v_mov_b32_e32 v112, v40
	v_mov_b32_e32 v113, v41
	v_mov_b32_e32 v114, v42
	v_mov_b32_e32 v115, v43
	v_lshlrev_b32_e32 v120, 16, v44
	v_and_b32_e32 v121, 0xffff0000, v44
	v_fmac_f32_e32 v108, v4, v120
	v_fmac_f32_e32 v109, v5, v121
	v_lshlrev_b32_e32 v120, 16, v45
	v_and_b32_e32 v121, 0xffff0000, v45
	v_fmac_f32_e32 v110, v6, v120
	v_fmac_f32_e32 v111, v7, v121
	v_lshlrev_b32_e32 v120, 16, v46
	v_and_b32_e32 v121, 0xffff0000, v46
	v_fmac_f32_e32 v112, v8, v120
	v_fmac_f32_e32 v113, v9, v121
	v_lshlrev_b32_e32 v120, 16, v47
	v_and_b32_e32 v121, 0xffff0000, v47
	v_fmac_f32_e32 v114, v10, v120
	v_fmac_f32_e32 v115, v11, v121
	v_lshlrev_b32_e32 v120, 16, v48
	v_and_b32_e32 v121, 0xffff0000, v48
	v_fmac_f32_e32 v108, v12, v120
	v_fmac_f32_e32 v109, v13, v121
	v_lshlrev_b32_e32 v120, 16, v49
	v_and_b32_e32 v121, 0xffff0000, v49
	v_fmac_f32_e32 v110, v14, v120
	v_fmac_f32_e32 v111, v15, v121
	v_lshlrev_b32_e32 v120, 16, v50
	v_and_b32_e32 v121, 0xffff0000, v50
	v_fmac_f32_e32 v112, v16, v120
	v_fmac_f32_e32 v113, v17, v121
	v_lshlrev_b32_e32 v120, 16, v51
	v_and_b32_e32 v121, 0xffff0000, v51
	v_fmac_f32_e32 v114, v18, v120
	v_fmac_f32_e32 v115, v19, v121
	v_lshlrev_b32_e32 v120, 16, v52
	v_and_b32_e32 v121, 0xffff0000, v52
	v_fmac_f32_e32 v108, v20, v120
	v_fmac_f32_e32 v109, v21, v121
	v_lshlrev_b32_e32 v120, 16, v53
	v_and_b32_e32 v121, 0xffff0000, v53
	v_fmac_f32_e32 v110, v22, v120
	v_fmac_f32_e32 v111, v23, v121
	v_lshlrev_b32_e32 v120, 16, v54
	v_and_b32_e32 v121, 0xffff0000, v54
	v_fmac_f32_e32 v112, v24, v120
	v_fmac_f32_e32 v113, v25, v121
	v_lshlrev_b32_e32 v120, 16, v55
	v_and_b32_e32 v121, 0xffff0000, v55
	v_fmac_f32_e32 v114, v26, v120
	v_fmac_f32_e32 v115, v27, v121
	v_lshlrev_b32_e32 v120, 16, v56
	v_and_b32_e32 v121, 0xffff0000, v56
	v_fmac_f32_e32 v108, v28, v120
	v_fmac_f32_e32 v109, v29, v121
	v_lshlrev_b32_e32 v120, 16, v57
	v_and_b32_e32 v121, 0xffff0000, v57
	v_fmac_f32_e32 v110, v30, v120
	v_fmac_f32_e32 v111, v31, v121
	v_lshlrev_b32_e32 v120, 16, v58
	v_and_b32_e32 v121, 0xffff0000, v58
	v_fmac_f32_e32 v112, v32, v120
	v_fmac_f32_e32 v113, v33, v121
	v_lshlrev_b32_e32 v120, 16, v59
	v_and_b32_e32 v121, 0xffff0000, v59
	v_fmac_f32_e32 v114, v34, v120
	v_fmac_f32_e32 v115, v35, v121
	v_cvt_pk_bf16_f32 v116, v108, v109
	v_cvt_pk_bf16_f32 v117, v110, v111
	v_cvt_pk_bf16_f32 v118, v112, v113
	v_cvt_pk_bf16_f32 v119, v114, v115
	s_lshr_b32 s13, s12, 6
	s_lshl_b32 s20, s13, 10
	s_add_u32 s22, s4, s20
	s_addc_u32 s23, s5, 0
	global_store_dwordx4 v3, v[116:119], s[22:23]
.Lmyconv_cskip0:
	s_add_u32 s12, s12, s7
	s_cmp_ge_u32 s12, 0x400000
	s_cbranch_scc1 .Lmyconv_cskip1
	v_mov_b32_e32 v108, v36
	v_mov_b32_e32 v109, v37
	v_mov_b32_e32 v110, v38
	v_mov_b32_e32 v111, v39
	v_mov_b32_e32 v112, v40
	v_mov_b32_e32 v113, v41
	v_mov_b32_e32 v114, v42
	v_mov_b32_e32 v115, v43
	v_lshlrev_b32_e32 v120, 16, v60
	v_and_b32_e32 v121, 0xffff0000, v60
	v_fmac_f32_e32 v108, v4, v120
	v_fmac_f32_e32 v109, v5, v121
	v_lshlrev_b32_e32 v120, 16, v61
	v_and_b32_e32 v121, 0xffff0000, v61
	v_fmac_f32_e32 v110, v6, v120
	v_fmac_f32_e32 v111, v7, v121
	v_lshlrev_b32_e32 v120, 16, v62
	v_and_b32_e32 v121, 0xffff0000, v62
	v_fmac_f32_e32 v112, v8, v120
	v_fmac_f32_e32 v113, v9, v121
	v_lshlrev_b32_e32 v120, 16, v63
	v_and_b32_e32 v121, 0xffff0000, v63
	v_fmac_f32_e32 v114, v10, v120
	v_fmac_f32_e32 v115, v11, v121
	v_lshlrev_b32_e32 v120, 16, v64
	v_and_b32_e32 v121, 0xffff0000, v64
	v_fmac_f32_e32 v108, v12, v120
	v_fmac_f32_e32 v109, v13, v121
	v_lshlrev_b32_e32 v120, 16, v65
	v_and_b32_e32 v121, 0xffff0000, v65
	v_fmac_f32_e32 v110, v14, v120
	v_fmac_f32_e32 v111, v15, v121
	v_lshlrev_b32_e32 v120, 16, v66
	v_and_b32_e32 v121, 0xffff0000, v66
	v_fmac_f32_e32 v112, v16, v120
	v_fmac_f32_e32 v113, v17, v121
	v_lshlrev_b32_e32 v120, 16, v67
	v_and_b32_e32 v121, 0xffff0000, v67
	v_fmac_f32_e32 v114, v18, v120
	v_fmac_f32_e32 v115, v19, v121
	v_lshlrev_b32_e32 v120, 16, v68
	v_and_b32_e32 v121, 0xffff0000, v68
	v_fmac_f32_e32 v108, v20, v120
	v_fmac_f32_e32 v109, v21, v121
	v_lshlrev_b32_e32 v120, 16, v69
	v_and_b32_e32 v121, 0xffff0000, v69
	v_fmac_f32_e32 v110, v22, v120
	v_fmac_f32_e32 v111, v23, v121
	v_lshlrev_b32_e32 v120, 16, v70
	v_and_b32_e32 v121, 0xffff0000, v70
	v_fmac_f32_e32 v112, v24, v120
	v_fmac_f32_e32 v113, v25, v121
	v_lshlrev_b32_e32 v120, 16, v71
	v_and_b32_e32 v121, 0xffff0000, v71
	v_fmac_f32_e32 v114, v26, v120
	v_fmac_f32_e32 v115, v27, v121
	v_lshlrev_b32_e32 v120, 16, v72
	v_and_b32_e32 v121, 0xffff0000, v72
	v_fmac_f32_e32 v108, v28, v120
	v_fmac_f32_e32 v109, v29, v121
	v_lshlrev_b32_e32 v120, 16, v73
	v_and_b32_e32 v121, 0xffff0000, v73
	v_fmac_f32_e32 v110, v30, v120
	v_fmac_f32_e32 v111, v31, v121
	v_lshlrev_b32_e32 v120, 16, v74
	v_and_b32_e32 v121, 0xffff0000, v74
	v_fmac_f32_e32 v112, v32, v120
	v_fmac_f32_e32 v113, v33, v121
	v_lshlrev_b32_e32 v120, 16, v75
	v_and_b32_e32 v121, 0xffff0000, v75
	v_fmac_f32_e32 v114, v34, v120
	v_fmac_f32_e32 v115, v35, v121
	v_cvt_pk_bf16_f32 v116, v108, v109
	v_cvt_pk_bf16_f32 v117, v110, v111
	v_cvt_pk_bf16_f32 v118, v112, v113
	v_cvt_pk_bf16_f32 v119, v114, v115
	s_lshr_b32 s13, s12, 6
	s_lshl_b32 s20, s13, 10
	s_add_u32 s22, s4, s20
	s_addc_u32 s23, s5, 0
	global_store_dwordx4 v3, v[116:119], s[22:23]
; __device__ __forceinline__ unsigned cvt_pk_bf16(float lo, float hi) { unsigned r; asm volatile("v_cvt_pk_bf16_f32 %0, %1, %2" : "=v"(r) : "v"(lo), "v"(hi)); return r; }
; __device__ __forceinline__ float bflo(unsigned w) { return __uint_as_float(w << 16); }
; __device__ __forceinline__ float bfhi(unsigned w) { return __uint_as_float(w & 0xffff0000u); }
; __device__ __forceinline__ unsigned xb_add(unsigned* p, unsigned v) { return __hip_atomic_fetch_add(p, v, __ATOMIC_RELAXED, __HIP_MEMORY_SCOPE_AGENT); }
; __device__ __forceinline__ void xcd_barrier_fast(const XcdBarrier& b) {
;     asm volatile("s_waitcnt vmcnt(0)" ::: "memory");
;     __syncthreads();
;     if (threadIdx.x == 0) {
;         unsigned* bar = b.bar;
;         __builtin_amdgcn_s_waitcnt(0);
;         unsigned nloc = b.st[0], nx = b.st[1];
;         const unsigned old = xb_add(&bar[XB_XSUB(b.x)], 1u);
;         const unsigned gen = old / nloc;
;         if (old + 1u == (gen + 1u) * nloc) {
; __global__ void __launch_bounds__(512, 2) mega_fwd(Params P) {
;     ...
;                         for (int q = 0; q < 4; ++q) { const size_t idx = idx0 + (size_t)q * GT; if (idx < (size_t)T_TOK * 64) { const int row = (int)(idx >> 6);
;                             f32x4 a0 = bb[0], a1 = bb[1];
; #pragma unroll
;                             for (int j = 0; j < 4; ++j) { const u32x4 v = xv[q][j]; f32x4 x0, x1; x0[0] = bflo(v.x); x0[1] = bfhi(v.x); x0[2] = bflo(v.y); x0[3] = bfhi(v.y); x1[0] = bflo(v.z); x1[1] = bfhi(v.z); x1[2] = bflo(v.w); x1[3] = bfhi(v.w);
;                                 a0 += wv[j][0] * x0; a1 += wv[j][1] * x1; }
;                             u32x4 o; o.x = cvt_pk_bf16(a0[0], a0[1]); o.y = cvt_pk_bf16(a0[2], a0[3]); o.z = cvt_pk_bf16(a1[0], a1[1]); o.w = cvt_pk_bf16(a1[2], a1[3]);
;                             *(u32x4*)(XC + (size_t)row * 512 + c0) = o; } }
;                       } }
.Lmyconv_cskip1:
	s_add_u32 s12, s12, s7
	s_cmp_ge_u32 s12, 0x400000
	s_cbranch_scc1 .Lmyconv_cskip2
	v_mov_b32_e32 v108, v36
	v_mov_b32_e32 v109, v37
	v_mov_b32_e32 v110, v38
	v_mov_b32_e32 v111, v39
	v_mov_b32_e32 v112, v40
	v_mov_b32_e32 v113, v41
	v_mov_b32_e32 v114, v42
	v_mov_b32_e32 v115, v43
	v_lshlrev_b32_e32 v120, 16, v76
	v_and_b32_e32 v121, 0xffff0000, v76
	v_fmac_f32_e32 v108, v4, v120
	v_fmac_f32_e32 v109, v5, v121
	v_lshlrev_b32_e32 v120, 16, v77
	v_and_b32_e32 v121, 0xffff0000, v77
	v_fmac_f32_e32 v110, v6, v120
	v_fmac_f32_e32 v111, v7, v121
	v_lshlrev_b32_e32 v120, 16, v78
	v_and_b32_e32 v121, 0xffff0000, v78
	v_fmac_f32_e32 v112, v8, v120
	v_fmac_f32_e32 v113, v9, v121
	v_lshlrev_b32_e32 v120, 16, v79
	v_and_b32_e32 v121, 0xffff0000, v79
	v_fmac_f32_e32 v114, v10, v120
	v_fmac_f32_e32 v115, v11, v121
	v_lshlrev_b32_e32 v120, 16, v80
	v_and_b32_e32 v121, 0xffff0000, v80
	v_fmac_f32_e32 v108, v12, v120
	v_fmac_f32_e32 v109, v13, v121
	v_lshlrev_b32_e32 v120, 16, v81
	v_and_b32_e32 v121, 0xffff0000, v81
	v_fmac_f32_e32 v110, v14, v120
	v_fmac_f32_e32 v111, v15, v121
	v_lshlrev_b32_e32 v120, 16, v82
	v_and_b32_e32 v121, 0xffff0000, v82
	v_fmac_f32_e32 v112, v16, v120
	v_fmac_f32_e32 v113, v17, v121
	v_lshlrev_b32_e32 v120, 16, v83
	v_and_b32_e32 v121, 0xffff0000, v83
	v_fmac_f32_e32 v114, v18, v120
	v_fmac_f32_e32 v115, v19, v121
	v_lshlrev_b32_e32 v120, 16, v84
	v_and_b32_e32 v121, 0xffff0000, v84
	v_fmac_f32_e32 v108, v20, v120
	v_fmac_f32_e32 v109, v21, v121
	v_lshlrev_b32_e32 v120, 16, v85
	v_and_b32_e32 v121, 0xffff0000, v85
	v_fmac_f32_e32 v110, v22, v120
	v_fmac_f32_e32 v111, v23, v121
	v_lshlrev_b32_e32 v120, 16, v86
	v_and_b32_e32 v121, 0xffff0000, v86
	v_fmac_f32_e32 v112, v24, v120
	v_fmac_f32_e32 v113, v25, v121
	v_lshlrev_b32_e32 v120, 16, v87
	v_and_b32_e32 v121, 0xffff0000, v87
	v_fmac_f32_e32 v114, v26, v120
	v_fmac_f32_e32 v115, v27, v121
	v_lshlrev_b32_e32 v120, 16, v88
	v_and_b32_e32 v121, 0xffff0000, v88
	v_fmac_f32_e32 v108, v28, v120
	v_fmac_f32_e32 v109, v29, v121
	v_lshlrev_b32_e32 v120, 16, v89
	v_and_b32_e32 v121, 0xffff0000, v89
	v_fmac_f32_e32 v110, v30, v120
	v_fmac_f32_e32 v111, v31, v121
	v_lshlrev_b32_e32 v120, 16, v90
	v_and_b32_e32 v121, 0xffff0000, v90
	v_fmac_f32_e32 v112, v32, v120
	v_fmac_f32_e32 v113, v33, v121
	v_lshlrev_b32_e32 v120, 16, v91
	v_and_b32_e32 v121, 0xffff0000, v91
	v_fmac_f32_e32 v114, v34, v120
	v_fmac_f32_e32 v115, v35, v121
	v_cvt_pk_bf16_f32 v116, v108, v109
	v_cvt_pk_bf16_f32 v117, v110, v111
	v_cvt_pk_bf16_f32 v118, v112, v113
	v_cvt_pk_bf16_f32 v119, v114, v115
	s_lshr_b32 s13, s12, 6
	s_lshl_b32 s20, s13, 10
	s_add_u32 s22, s4, s20
	s_addc_u32 s23, s5, 0
	global_store_dwordx4 v3, v[116:119], s[22:23]
.Lmyconv_cskip2:
	s_add_u32 s12, s12, s7
	s_cmp_ge_u32 s12, 0x400000
	s_cbranch_scc1 .Lmyconv_cskip3
	v_mov_b32_e32 v108, v36
	v_mov_b32_e32 v109, v37
	v_mov_b32_e32 v110, v38
	v_mov_b32_e32 v111, v39
	v_mov_b32_e32 v112, v40
	v_mov_b32_e32 v113, v41
	v_mov_b32_e32 v114, v42
	v_mov_b32_e32 v115, v43
	v_lshlrev_b32_e32 v120, 16, v92
	v_and_b32_e32 v121, 0xffff0000, v92
	v_fmac_f32_e32 v108, v4, v120
	v_fmac_f32_e32 v109, v5, v121
	v_lshlrev_b32_e32 v120, 16, v93
	v_and_b32_e32 v121, 0xffff0000, v93
	v_fmac_f32_e32 v110, v6, v120
	v_fmac_f32_e32 v111, v7, v121
	v_lshlrev_b32_e32 v120, 16, v94
	v_and_b32_e32 v121, 0xffff0000, v94
	v_fmac_f32_e32 v112, v8, v120
	v_fmac_f32_e32 v113, v9, v121
	v_lshlrev_b32_e32 v120, 16, v95
	v_and_b32_e32 v121, 0xffff0000, v95
	v_fmac_f32_e32 v114, v10, v120
	v_fmac_f32_e32 v115, v11, v121
	v_lshlrev_b32_e32 v120, 16, v96
	v_and_b32_e32 v121, 0xffff0000, v96
	v_fmac_f32_e32 v108, v12, v120
	v_fmac_f32_e32 v109, v13, v121
	v_lshlrev_b32_e32 v120, 16, v97
	v_and_b32_e32 v121, 0xffff0000, v97
	v_fmac_f32_e32 v110, v14, v120
	v_fmac_f32_e32 v111, v15, v121
	v_lshlrev_b32_e32 v120, 16, v98
	v_and_b32_e32 v121, 0xffff0000, v98
	v_fmac_f32_e32 v112, v16, v120
	v_fmac_f32_e32 v113, v17, v121
	v_lshlrev_b32_e32 v120, 16, v99
	v_and_b32_e32 v121, 0xffff0000, v99
	v_fmac_f32_e32 v114, v18, v120
	v_fmac_f32_e32 v115, v19, v121
	v_lshlrev_b32_e32 v120, 16, v100
	v_and_b32_e32 v121, 0xffff0000, v100
	v_fmac_f32_e32 v108, v20, v120
	v_fmac_f32_e32 v109, v21, v121
	v_lshlrev_b32_e32 v120, 16, v101
	v_and_b32_e32 v121, 0xffff0000, v101
	v_fmac_f32_e32 v110, v22, v120
	v_fmac_f32_e32 v111, v23, v121
	v_lshlrev_b32_e32 v120, 16, v102
	v_and_b32_e32 v121, 0xffff0000, v102
	v_fmac_f32_e32 v112, v24, v120
	v_fmac_f32_e32 v113, v25, v121
	v_lshlrev_b32_e32 v120, 16, v103
	v_and_b32_e32 v121, 0xffff0000, v103
	v_fmac_f32_e32 v114, v26, v120
	v_fmac_f32_e32 v115, v27, v121
	v_lshlrev_b32_e32 v120, 16, v104
	v_and_b32_e32 v121, 0xffff0000, v104
	v_fmac_f32_e32 v108, v28, v120
	v_fmac_f32_e32 v109, v29, v121
	v_lshlrev_b32_e32 v120, 16, v105
	v_and_b32_e32 v121, 0xffff0000, v105
	v_fmac_f32_e32 v110, v30, v120
	v_fmac_f32_e32 v111, v31, v121
	v_lshlrev_b32_e32 v120, 16, v106
	v_and_b32_e32 v121, 0xffff0000, v106
	v_fmac_f32_e32 v112, v32, v120
	v_fmac_f32_e32 v113, v33, v121
	v_lshlrev_b32_e32 v120, 16, v107
	v_and_b32_e32 v121, 0xffff0000, v107
	v_fmac_f32_e32 v114, v34, v120
	v_fmac_f32_e32 v115, v35, v121
	v_cvt_pk_bf16_f32 v116, v108, v109
	v_cvt_pk_bf16_f32 v117, v110, v111
	v_cvt_pk_bf16_f32 v118, v112, v113
	v_cvt_pk_bf16_f32 v119, v114, v115
	s_lshr_b32 s13, s12, 6
	s_lshl_b32 s20, s13, 10
	s_add_u32 s22, s4, s20
	s_addc_u32 s23, s5, 0
	global_store_dwordx4 v3, v[116:119], s[22:23]
.Lmyconv_cskip3:
	s_lshl_b32 s12, s7, 2
	s_add_u32 s6, s6, s12
	s_cmp_lt_u32 s6, 0x400000
	s_cbranch_scc1 .Lmyconv_loop
.Lmyconv_done:
.LBB0_956:
	s_or_b64 exec, exec, s[40:41]
	s_getreg_b32 s1, hwreg(HW_REG_XCC_ID, 0, 4)
	s_waitcnt vmcnt(0)
	s_waitcnt lgkmcnt(0)
	s_barrier
	s_and_saveexec_b64 s[2:3], s[84:85]
	s_cbranch_execz .LBB0_1018
	v_readlane_b32 s4, v255, 10
	s_waitcnt vmcnt(0) expcnt(0) lgkmcnt(0)
	s_mov_b64 s[6:7], exec
	v_mov_b32_e32 v0, s4
	v_readlane_b32 s4, v255, 11
	ds_read_b32 v3, v0
	s_lshl_b32 s1, s1, 8
	v_mov_b32_e32 v0, s4
	ds_read_b32 v2, v0
	v_readlane_b32 s8, v254, 3
	s_and_b32 s1, s1, 0xf00
	v_readlane_b32 s10, v254, 5
	v_mbcnt_lo_u32_b32 v0, s6, 0
	v_readlane_b32 s11, v254, 6
	s_add_u32 s4, s10, s1
	v_mbcnt_hi_u32_b32 v0, s7, v0
	v_readlane_b32 s9, v254, 4
	s_addc_u32 s5, s11, 0
	v_cmp_eq_u32_e32 vcc, 0, v0
	s_and_saveexec_b64 s[8:9], vcc
	s_cbranch_execz .LBB0_959
	s_bcnt1_i32_b64 s1, s[6:7]
	v_mov_b32_e32 v4, s1
	v_mov_b32_e32 v5, 0x1000
	global_atomic_add v4, v5, v4, s[4:5] offset:1024 sc0
